# GLA pass C epilogue: the four norm-gain loads issued together (no load-wait-store ladder) and 4 dwordx2 stores widened to 2 dwordx4 via permlane32_swap
# speedup vs baseline: 1.0064x; 1.0018x over previous
.LBB0_504:
	s_or_b64 exec, exec, s[2:3]
	v_or_b32_e32 v20, s48, v52
	v_ashrrev_i32_e32 v21, 31, v20
	v_lshl_add_u64 v[22:23], v[20:21], 2, s[60:61]
	s_waitcnt lgkmcnt(0)
	s_barrier
	global_load_dwordx4 v[16:19], v[22:23], off
	global_load_dwordx4 v[100:103], v[22:23], off offset:32
	global_load_dwordx4 v[104:107], v[22:23], off offset:64
	global_load_dwordx4 v[108:111], v[22:23], off offset:96
	s_add_i32 s2, s5, 0
	s_waitcnt vmcnt(7)
	v_lshlrev_b32_e32 v24, 16, v64
	v_and_b32_e32 v25, 0xffff0000, v64
	v_lshlrev_b32_e32 v26, 16, v65
	v_and_b32_e32 v27, 0xffff0000, v65
	v_lshl_add_u32 v30, v68, 2, s2
	v_mul_f32_e32 v31, 0xbfb8aa3b, v24
	v_mul_f32_e32 v32, 0xbfb8aa3b, v25
	v_mul_f32_e32 v33, 0xbfb8aa3b, v26
	v_mul_f32_e32 v34, 0xbfb8aa3b, v27
	v_add_u32_e32 v35, 0x1a000, v30
	v_exp_f32_e32 v36, v31
	v_exp_f32_e32 v37, v32
	v_exp_f32_e32 v38, v33
	v_exp_f32_e32 v34, v34
	ds_read2_b32 v[30:31], v35 offset1:32
	ds_read2_b32 v[32:33], v35 offset0:64 offset1:96
	v_add_f32_e32 v35, 1.0, v36
	v_add_f32_e32 v36, 1.0, v37
	v_add_f32_e32 v37, 1.0, v38
	v_add_f32_e32 v38, 1.0, v34
	v_rcp_f32_e32 v34, v35
	v_rcp_f32_e32 v35, v36
	v_rcp_f32_e32 v36, v37
	v_rcp_f32_e32 v37, v38
	s_waitcnt lgkmcnt(1)
	v_mov_b32_e32 v38, v30
	s_waitcnt lgkmcnt(0)
	v_mov_b32_e32 v39, v32
	v_mov_b32_e32 v32, v31
	v_pk_add_f32 v[30:31], v[38:39], v[32:33]
	v_ashrrev_i32_e32 v63, 31, v62
	v_add_f32_e32 v30, v30, v31
	v_fmamk_f32 v30, v30, 0x3c000000, v66
	v_mul_f32_e32 v31, 0x4b800000, v30
	v_cmp_gt_f32_e32 vcc, s58, v30
	v_lshlrev_b64 v[28:29], 11, v[62:63]
	s_lshl_b32 s46, s4, 1
	v_cndmask_b32_e32 v30, v30, v31, vcc
	v_rsq_f32_e32 v30, v30
	v_lshl_add_u64 v[28:29], s[44:45], 0, v[28:29]
	v_lshl_add_u64 v[28:29], v[28:29], 0, s[46:47]
	v_lshl_add_u64 v[20:21], v[20:21], 1, v[28:29]
	v_and_b32_e32 v120, 32, v188
	v_lshrrev_b32_e32 v120, 2, v120
	v_mov_b32_e32 v121, 0
	v_lshl_add_u64 v[122:123], v[20:21], 0, v[120:121]
	v_mul_f32_e32 v28, 0x45800000, v30
	v_cndmask_b32_e32 v28, v30, v28, vcc
	v_pk_mul_f32 v[0:1], v[0:1], v[28:29] op_sel_hi:[1,0]
	v_pk_mul_f32 v[2:3], v[2:3], v[28:29] op_sel_hi:[1,0]
	v_pk_mul_f32 v[24:25], v[34:35], v[24:25]
	v_pk_mul_f32 v[26:27], v[36:37], v[26:27]
	v_pk_mul_f32 v[4:5], v[4:5], v[28:29] op_sel_hi:[1,0]
	v_pk_mul_f32 v[6:7], v[6:7], v[28:29] op_sel_hi:[1,0]
	v_pk_mul_f32 v[8:9], v[8:9], v[28:29] op_sel_hi:[1,0]
	v_pk_mul_f32 v[10:11], v[10:11], v[28:29] op_sel_hi:[1,0]
	s_add_i32 s59, s59, s78
	s_cmpk_lt_i32 s59, 0x800
	s_waitcnt vmcnt(0)
	v_pk_mul_f32 v[0:1], v[16:17], v[0:1]
	v_pk_mul_f32 v[2:3], v[18:19], v[2:3]
	v_pk_mul_f32 v[0:1], v[24:25], v[0:1]
	v_pk_mul_f32 v[2:3], v[26:27], v[2:3]
	v_cvt_pk_bf16_f32 v112, v0, v1
	v_cvt_pk_bf16_f32 v113, v2, v3
	v_lshlrev_b32_e32 v16, 16, v60
	v_and_b32_e32 v17, 0xffff0000, v60
	v_lshlrev_b32_e32 v18, 16, v61
	v_and_b32_e32 v19, 0xffff0000, v61
	v_mul_f32_e32 v24, 0xbfb8aa3b, v16
	v_mul_f32_e32 v25, 0xbfb8aa3b, v17
	v_mul_f32_e32 v26, 0xbfb8aa3b, v18
	v_mul_f32_e32 v27, 0xbfb8aa3b, v19
	v_exp_f32_e32 v24, v24
	v_exp_f32_e32 v25, v25
	v_exp_f32_e32 v26, v26
	v_exp_f32_e32 v27, v27
	v_add_f32_e32 v24, 1.0, v24
	v_add_f32_e32 v25, 1.0, v25
	v_add_f32_e32 v26, 1.0, v26
	v_add_f32_e32 v27, 1.0, v27
	v_rcp_f32_e32 v24, v24
	v_rcp_f32_e32 v25, v25
	v_rcp_f32_e32 v26, v26
	v_rcp_f32_e32 v27, v27
	v_pk_mul_f32 v[16:17], v[24:25], v[16:17]
	v_pk_mul_f32 v[18:19], v[26:27], v[18:19]
	v_pk_mul_f32 v[0:1], v[100:101], v[4:5]
	v_pk_mul_f32 v[2:3], v[102:103], v[6:7]
	v_pk_mul_f32 v[0:1], v[16:17], v[0:1]
	v_pk_mul_f32 v[2:3], v[18:19], v[2:3]
	v_cvt_pk_bf16_f32 v114, v0, v1
	v_cvt_pk_bf16_f32 v115, v2, v3
	s_nop 1
	v_permlane32_swap_b32_e32 v112, v114
	v_permlane32_swap_b32_e32 v113, v115
	global_store_dwordx4 v[122:123], v[112:115], off
	v_lshlrev_b32_e32 v4, 16, v58
	v_and_b32_e32 v5, 0xffff0000, v58
	v_lshlrev_b32_e32 v6, 16, v59
	v_and_b32_e32 v7, 0xffff0000, v59
	v_mul_f32_e32 v16, 0xbfb8aa3b, v4
	v_mul_f32_e32 v17, 0xbfb8aa3b, v5
	v_mul_f32_e32 v18, 0xbfb8aa3b, v6
	v_mul_f32_e32 v19, 0xbfb8aa3b, v7
	v_exp_f32_e32 v16, v16
	v_exp_f32_e32 v17, v17
	v_exp_f32_e32 v18, v18
	v_exp_f32_e32 v19, v19
	v_add_f32_e32 v16, 1.0, v16
	v_add_f32_e32 v17, 1.0, v17
	v_add_f32_e32 v18, 1.0, v18
	v_add_f32_e32 v19, 1.0, v19
	v_rcp_f32_e32 v16, v16
	v_rcp_f32_e32 v17, v17
	v_rcp_f32_e32 v18, v18
	v_rcp_f32_e32 v19, v19
	v_pk_mul_f32 v[4:5], v[16:17], v[4:5]
	v_pk_mul_f32 v[6:7], v[18:19], v[6:7]
	v_pk_mul_f32 v[0:1], v[104:105], v[8:9]
	v_pk_mul_f32 v[2:3], v[106:107], v[10:11]
	v_pk_mul_f32 v[0:1], v[4:5], v[0:1]
	v_pk_mul_f32 v[2:3], v[6:7], v[2:3]
	v_cvt_pk_bf16_f32 v116, v0, v1
	v_cvt_pk_bf16_f32 v117, v2, v3
	v_lshlrev_b32_e32 v4, 16, v56
	v_and_b32_e32 v5, 0xffff0000, v56
	v_lshlrev_b32_e32 v6, 16, v57
	v_and_b32_e32 v7, 0xffff0000, v57
	v_mul_f32_e32 v8, 0xbfb8aa3b, v4
	v_mul_f32_e32 v9, 0xbfb8aa3b, v5
	v_mul_f32_e32 v10, 0xbfb8aa3b, v6
	v_mul_f32_e32 v11, 0xbfb8aa3b, v7
	v_exp_f32_e32 v8, v8
	v_exp_f32_e32 v9, v9
	v_exp_f32_e32 v10, v10
	v_exp_f32_e32 v11, v11
	v_add_f32_e32 v8, 1.0, v8
	v_add_f32_e32 v9, 1.0, v9
	v_add_f32_e32 v10, 1.0, v10
	v_add_f32_e32 v11, 1.0, v11
	v_rcp_f32_e32 v8, v8
	v_rcp_f32_e32 v9, v9
	v_rcp_f32_e32 v10, v10
	v_rcp_f32_e32 v11, v11
	v_pk_mul_f32 v[4:5], v[8:9], v[4:5]
	v_pk_mul_f32 v[8:9], v[12:13], v[28:29] op_sel_hi:[1,0]
	v_pk_mul_f32 v[6:7], v[10:11], v[6:7]
	v_pk_mul_f32 v[10:11], v[14:15], v[28:29] op_sel_hi:[1,0]
	v_pk_mul_f32 v[0:1], v[108:109], v[8:9]
	v_pk_mul_f32 v[2:3], v[110:111], v[10:11]
	v_pk_mul_f32 v[0:1], v[4:5], v[0:1]
	v_pk_mul_f32 v[2:3], v[6:7], v[2:3]
	v_cvt_pk_bf16_f32 v118, v0, v1
	v_cvt_pk_bf16_f32 v119, v2, v3
	s_nop 1
	v_permlane32_swap_b32_e32 v116, v118
	v_permlane32_swap_b32_e32 v117, v119
	global_store_dwordx4 v[122:123], v[116:119], off offset:32
	s_barrier
	s_cbranch_scc0 .LBB0_517
